# static priority raise applied to waves 0-3 instead of 4-7 in the attention phases (per-half comparison)
# speedup vs baseline: 1.0018x; 1.0018x over previous
; template <int MASK> __global__ void __launch_bounds__(512, 2) mega_fwd(Args a) {
;     ...
;     for (int ph = a.ph_lo; ph < a.ph_hi; ++ph) {
;     ...
;         KA ka; ka.k = (kptr_t)__builtin_amdgcn_kernarg_segment_ptr(); asm volatile("" : "+s"(ka.k));
;         ka.ws = *(unsigned char* const __attribute__((address_space(4)))*)(ka.k + 256); float* outp = *(float* const __attribute__((address_space(4)))*)(ka.k + 248);
;         ka.outb = (unsigned char*)outp;
;         unsigned char* ws = ka.ws;
;         float* rss = (float*)(ws + WS_RSS); bf16_t* xb = (bf16_t*)(ws + WS_XB); bf16_t* Hb = (bf16_t*)(ws + WS_H);
;         for (int rep = 0; rep < ((ph == PROBE_PH) ? 2 : 1); ++rep) {
;         int kind, arg = 0;
;         switch (ph) {
;             case 0: kind = 0; break;
;             case 1: kind = 1; arg = 0; break;    case 2: kind = 2; arg = 0; break;
;             case 3: kind = 3; arg = 0; break;    case 4: kind = 4; break;   case 5: kind = 5; break;   case 6: kind = 6; break;
;             case 7: kind = 2; arg = 4; break;
;             case 8: kind = 1; arg = 1; break;    case 9: kind = 2; arg = 1; break;
;             case 10: kind = 1; arg = 2; break;   case 11: kind = 2; arg = 2; break;
;             case 12: kind = 3; arg = 1; break;   case 13: kind = 7; break;  case 14: kind = 8; break;
;             case 15: kind = 2; arg = 5; break;
;             case 16: kind = 1; arg = 3; break;   default: kind = 2; arg = 3; break;
;         }
.LBB0_24:
	v_writelane_b32 v254, s0, 61
	v_readlane_b32 s8, v253, 51
	s_mov_b64 s[4:5], 0
	v_writelane_b32 v254, s1, 62
	s_mov_b64 s[0:1], -1
	v_readlane_b32 s9, v253, 52
	v_readlane_b32 s10, v253, 53
	v_readlane_b32 s11, v253, 54
	s_setprio 0
	v_readfirstlane_b32 s100, v240
	s_nop 3
	s_lshr_b32 s100, s100, 8
	s_cmp_lg_u32 s100, 0
	s_cbranch_scc1 .Lprio_done
	s_cmp_eq_u32 s8, 5
	s_cbranch_scc1 .Lprio_set
	s_cmp_eq_u32 s8, 14
	s_cbranch_scc0 .Lprio_done
